# select search: the smallest-key scan of the negative-threshold case only visits the registers that hold keys
# speedup vs baseline: 1.0068x; 1.0032x over previous
; #define DPPU(v, ctrl, rm) (unsigned)__builtin_amdgcn_update_dpp(0, (int)(v), ctrl, rm, 0xf, false)
; __device__ __forceinline__ unsigned wave_umax(unsigned v) {
;     ...
;     v = max(v, DPPU(v, 0x111, 0xf)); v = max(v, DPPU(v, 0x112, 0xf)); v = max(v, DPPU(v, 0x114, 0xf)); v = max(v, DPPU(v, 0x118, 0xf));
;     v = max(v, DPPU(v, 0x142, 0xa)); v = max(v, DPPU(v, 0x143, 0xc));
;     return (unsigned)__builtin_amdgcn_readlane((int)v, 63);
; __device__ __forceinline__ void select_query(const unsigned (&u)[64], unsigned vmax, int q, int b, int lane, unsigned* MASKb) {
;     ...
;                 unsigned vmin = 0xffffffffu;
; #pragma unroll
;                 for (int i = 0; i < 64; ++i) vmin = min(vmin, u[i] - 1u);
;                 lo = ~wave_umax(~vmin) + 1u; Llo = __log2f((float)n) - L256; hi = K0; Lhi = L256 - __log2f(fmaxf((float)c0, 0.5f));
.Lsqa_s1lt:
	v_mov_b32_e32 v191, -1
	v_add_u32_e32 v0, -1, v138
	v_min_u32_e32 v191, v191, v0
	v_add_u32_e32 v0, -1, v140
	v_min_u32_e32 v191, v191, v0
	v_add_u32_e32 v0, -1, v139
	v_min_u32_e32 v191, v191, v0
	v_add_u32_e32 v0, -1, v141
	v_min_u32_e32 v191, v191, v0
	v_add_u32_e32 v0, -1, v142
	v_min_u32_e32 v191, v191, v0
	v_add_u32_e32 v0, -1, v146
	v_min_u32_e32 v191, v191, v0
	v_add_u32_e32 v0, -1, v143
	v_min_u32_e32 v191, v191, v0
	v_add_u32_e32 v0, -1, v147
	v_min_u32_e32 v191, v191, v0
	s_cmp_eq_u32 s32, 1
	s_cbranch_scc1 .Lsqa_vmd
	v_add_u32_e32 v0, -1, v144
	v_min_u32_e32 v191, v191, v0
	v_add_u32_e32 v0, -1, v148
	v_min_u32_e32 v191, v191, v0
	v_add_u32_e32 v0, -1, v145
	v_min_u32_e32 v191, v191, v0
	v_add_u32_e32 v0, -1, v149
	v_min_u32_e32 v191, v191, v0
	v_add_u32_e32 v0, -1, v150
	v_min_u32_e32 v191, v191, v0
	v_add_u32_e32 v0, -1, v152
	v_min_u32_e32 v191, v191, v0
	v_add_u32_e32 v0, -1, v151
	v_min_u32_e32 v191, v191, v0
	v_add_u32_e32 v0, -1, v154
	v_min_u32_e32 v191, v191, v0
	s_cmp_eq_u32 s32, 2
	s_cbranch_scc1 .Lsqa_vmd
	v_add_u32_e32 v0, -1, v153
	v_min_u32_e32 v191, v191, v0
	v_add_u32_e32 v0, -1, v156
	v_min_u32_e32 v191, v191, v0
	v_add_u32_e32 v0, -1, v155
	v_min_u32_e32 v191, v191, v0
	v_add_u32_e32 v0, -1, v157
	v_min_u32_e32 v191, v191, v0
	v_add_u32_e32 v0, -1, v158
	v_min_u32_e32 v191, v191, v0
	v_add_u32_e32 v0, -1, v160
	v_min_u32_e32 v191, v191, v0
	v_add_u32_e32 v0, -1, v159
	v_min_u32_e32 v191, v191, v0
	v_add_u32_e32 v0, -1, v161
	v_min_u32_e32 v191, v191, v0
	v_add_u32_e32 v0, -1, v167
	v_min_u32_e32 v191, v191, v0
	v_add_u32_e32 v0, -1, v169
	v_min_u32_e32 v191, v191, v0
	v_add_u32_e32 v0, -1, v168
	v_min_u32_e32 v191, v191, v0
	v_add_u32_e32 v0, -1, v170
	v_min_u32_e32 v191, v191, v0
	v_add_u32_e32 v0, -1, v173
	v_min_u32_e32 v191, v191, v0
	v_add_u32_e32 v0, -1, v174
	v_min_u32_e32 v191, v191, v0
	v_add_u32_e32 v0, -1, v175
	v_min_u32_e32 v191, v191, v0
	v_add_u32_e32 v0, -1, v176
	v_min_u32_e32 v191, v191, v0
	s_cmp_eq_u32 s32, 3
	s_cbranch_scc1 .Lsqa_vmd
	v_add_u32_e32 v0, -1, v76
	v_min_u32_e32 v191, v191, v0
	v_add_u32_e32 v0, -1, v78
	v_min_u32_e32 v191, v191, v0
	v_add_u32_e32 v0, -1, v77
	v_min_u32_e32 v191, v191, v0
	v_add_u32_e32 v0, -1, v79
	v_min_u32_e32 v191, v191, v0
	v_add_u32_e32 v0, -1, v80
	v_min_u32_e32 v191, v191, v0
	v_add_u32_e32 v0, -1, v84
	v_min_u32_e32 v191, v191, v0
	v_add_u32_e32 v0, -1, v81
	v_min_u32_e32 v191, v191, v0
	v_add_u32_e32 v0, -1, v85
	v_min_u32_e32 v191, v191, v0
	s_cmp_eq_u32 s32, 4
	s_cbranch_scc1 .Lsqa_vmd
	v_add_u32_e32 v0, -1, v82
	v_min_u32_e32 v191, v191, v0
	v_add_u32_e32 v0, -1, v86
	v_min_u32_e32 v191, v191, v0
	v_add_u32_e32 v0, -1, v83
	v_min_u32_e32 v191, v191, v0
	v_add_u32_e32 v0, -1, v87
	v_min_u32_e32 v191, v191, v0
	v_add_u32_e32 v0, -1, v89
	v_min_u32_e32 v191, v191, v0
	v_add_u32_e32 v0, -1, v91
	v_min_u32_e32 v191, v191, v0
	v_add_u32_e32 v0, -1, v90
	v_min_u32_e32 v191, v191, v0
	v_add_u32_e32 v0, -1, v93
	v_min_u32_e32 v191, v191, v0
	s_cmp_eq_u32 s32, 5
	s_cbranch_scc1 .Lsqa_vmd
	v_add_u32_e32 v0, -1, v92
	v_min_u32_e32 v191, v191, v0
	v_add_u32_e32 v0, -1, v95
	v_min_u32_e32 v191, v191, v0
	v_add_u32_e32 v0, -1, v94
	v_min_u32_e32 v191, v191, v0
	v_add_u32_e32 v0, -1, v96
	v_min_u32_e32 v191, v191, v0
	v_add_u32_e32 v0, -1, v97
	v_min_u32_e32 v191, v191, v0
	v_add_u32_e32 v0, -1, v172
	v_min_u32_e32 v191, v191, v0
	v_add_u32_e32 v0, -1, v171
	v_min_u32_e32 v191, v191, v0
	v_add_u32_e32 v0, -1, v178
	v_min_u32_e32 v191, v191, v0
	v_add_u32_e32 v0, -1, v180
	v_min_u32_e32 v191, v191, v0
	v_add_u32_e32 v0, -1, v183
	v_min_u32_e32 v191, v191, v0
	v_add_u32_e32 v0, -1, v182
	v_min_u32_e32 v191, v191, v0
	v_add_u32_e32 v0, -1, v184
	v_min_u32_e32 v191, v191, v0
	v_add_u32_e32 v0, -1, v186
	v_min_u32_e32 v191, v191, v0
	v_add_u32_e32 v0, -1, v187
	v_min_u32_e32 v191, v191, v0
	v_add_u32_e32 v0, -1, v188
	v_min_u32_e32 v191, v191, v0
	v_add_u32_e32 v0, -1, v189
	v_min_u32_e32 v191, v191, v0
.Lsqa_vmd:
	v_not_b32_e32 v191, v191
	s_nop 1
	v_max_u32_dpp v191, v191, v191 row_shr:1 row_mask:0xf bank_mask:0xf bound_ctrl:1
	s_nop 1
	v_max_u32_dpp v191, v191, v191 row_shr:2 row_mask:0xf bank_mask:0xf bound_ctrl:1
	s_nop 1
	v_max_u32_dpp v191, v191, v191 row_shr:4 row_mask:0xf bank_mask:0xf bound_ctrl:1
	s_nop 1
	v_max_u32_dpp v191, v191, v191 row_shr:8 row_mask:0xf bank_mask:0xf bound_ctrl:1
	s_nop 1
	v_max_u32_dpp v191, v191, v191 row_bcast:15 row_mask:0xa bank_mask:0xf
	s_nop 1
	v_max_u32_dpp v191, v191, v191 row_bcast:31 row_mask:0xc bank_mask:0xf
	s_nop 0
	v_readlane_b32 s26, v191, 63
	s_sub_i32 s13, 0, s26
	s_mov_b32 s12, 0x80000000
	s_mov_b32 s15, s24
	s_add_i32 s26, s75, 1
	s_mov_b32 s98, s26
	s_mov_b32 s99, 1
	s_sub_i32 s27, s26, 0x100
	v_cvt_f32_u32_e32 v202, s27
	s_sub_i32 s27, s26, s24
	v_cvt_f32_u32_e32 v36, s27
	v_add_f32_e32 v202, 0.5, v202
	v_add_f32_e32 v36, 0.5, v36
	v_log_f32_e32 v202, v202
	v_log_f32_e32 v36, v36
	s_not_b32 s27, s13
	s_and_b32 s27, s27, 0x7fffffff
	s_bfe_u32 s28, s27, 0x80017
	s_sub_u32 s28, s28, 0x43
	s_cmp_lt_u32 s28, 0x79
	s_cselect_b32 s101, 1, 0
	v_add_f32_e32 v35, 1.0, v202
	v_sub_f32_e32 v36, v36, v202
	v_sqrt_f32_e32 v192, s27
	v_mov_b32_e32 v193, 0
	v_mul_f32_e32 v192, s27, v192
	s_mov_b32 s22, 0
	s_mov_b32 s23, 0
	s_mov_b32 s21, 2
	s_branch .Lsqa_next

; #define DPPU(v, ctrl, rm) (unsigned)__builtin_amdgcn_update_dpp(0, (int)(v), ctrl, rm, 0xf, false)
; __device__ __forceinline__ unsigned wave_umax(unsigned v) {
;     ...
;     v = max(v, DPPU(v, 0x111, 0xf)); v = max(v, DPPU(v, 0x112, 0xf)); v = max(v, DPPU(v, 0x114, 0xf)); v = max(v, DPPU(v, 0x118, 0xf));
;     v = max(v, DPPU(v, 0x142, 0xa)); v = max(v, DPPU(v, 0x143, 0xc));
;     return (unsigned)__builtin_amdgcn_readlane((int)v, 63);
; __device__ __forceinline__ void select_query(const unsigned (&u)[64], unsigned vmax, int q, int b, int lane, unsigned* MASKb) {
;     ...
;                 unsigned vmin = 0xffffffffu;
; #pragma unroll
;                 for (int i = 0; i < 64; ++i) vmin = min(vmin, u[i] - 1u);
;                 lo = ~wave_umax(~vmin) + 1u; Llo = __log2f((float)n) - L256; hi = K0; Lhi = L256 - __log2f(fmaxf((float)c0, 0.5f));
.Lsqb_s1lt:
	v_mov_b32_e32 v142, -1
	v_add_u32_e32 v138, -1, v98
	v_min_u32_e32 v142, v142, v138
	v_add_u32_e32 v138, -1, v107
	v_min_u32_e32 v142, v142, v138
	v_add_u32_e32 v138, -1, v99
	v_min_u32_e32 v142, v142, v138
	v_add_u32_e32 v138, -1, v108
	v_min_u32_e32 v142, v142, v138
	v_add_u32_e32 v138, -1, v109
	v_min_u32_e32 v142, v142, v138
	v_add_u32_e32 v138, -1, v113
	v_min_u32_e32 v142, v142, v138
	v_add_u32_e32 v138, -1, v110
	v_min_u32_e32 v142, v142, v138
	v_add_u32_e32 v138, -1, v114
	v_min_u32_e32 v142, v142, v138
	s_cmp_eq_u32 s32, 1
	s_cbranch_scc1 .Lsqb_vmd
	v_add_u32_e32 v138, -1, v111
	v_min_u32_e32 v142, v142, v138
	v_add_u32_e32 v138, -1, v115
	v_min_u32_e32 v142, v142, v138
	v_add_u32_e32 v138, -1, v112
	v_min_u32_e32 v142, v142, v138
	v_add_u32_e32 v138, -1, v116
	v_min_u32_e32 v142, v142, v138
	v_add_u32_e32 v138, -1, v117
	v_min_u32_e32 v142, v142, v138
	v_add_u32_e32 v138, -1, v119
	v_min_u32_e32 v142, v142, v138
	v_add_u32_e32 v138, -1, v118
	v_min_u32_e32 v142, v142, v138
	v_add_u32_e32 v138, -1, v121
	v_min_u32_e32 v142, v142, v138
	s_cmp_eq_u32 s32, 2
	s_cbranch_scc1 .Lsqb_vmd
	v_add_u32_e32 v138, -1, v120
	v_min_u32_e32 v142, v142, v138
	v_add_u32_e32 v138, -1, v123
	v_min_u32_e32 v142, v142, v138
	v_add_u32_e32 v138, -1, v122
	v_min_u32_e32 v142, v142, v138
	v_add_u32_e32 v138, -1, v124
	v_min_u32_e32 v142, v142, v138
	v_add_u32_e32 v138, -1, v125
	v_min_u32_e32 v142, v142, v138
	v_add_u32_e32 v138, -1, v127
	v_min_u32_e32 v142, v142, v138
	v_add_u32_e32 v138, -1, v126
	v_min_u32_e32 v142, v142, v138
	v_add_u32_e32 v138, -1, v128
	v_min_u32_e32 v142, v142, v138
	v_add_u32_e32 v138, -1, v129
	v_min_u32_e32 v142, v142, v138
	v_add_u32_e32 v138, -1, v131
	v_min_u32_e32 v142, v142, v138
	v_add_u32_e32 v138, -1, v130
	v_min_u32_e32 v142, v142, v138
	v_add_u32_e32 v138, -1, v132
	v_min_u32_e32 v142, v142, v138
	v_add_u32_e32 v138, -1, v133
	v_min_u32_e32 v142, v142, v138
	v_add_u32_e32 v138, -1, v134
	v_min_u32_e32 v142, v142, v138
	v_add_u32_e32 v138, -1, v136
	v_min_u32_e32 v142, v142, v138
	v_add_u32_e32 v138, -1, v137
	v_min_u32_e32 v142, v142, v138
	s_cmp_eq_u32 s32, 3
	s_cbranch_scc1 .Lsqb_vmd
	v_add_u32_e32 v138, -1, v46
	v_min_u32_e32 v142, v142, v138
	v_add_u32_e32 v138, -1, v48
	v_min_u32_e32 v142, v142, v138
	v_add_u32_e32 v138, -1, v47
	v_min_u32_e32 v142, v142, v138
	v_add_u32_e32 v138, -1, v49
	v_min_u32_e32 v142, v142, v138
	v_add_u32_e32 v138, -1, v42
	v_min_u32_e32 v142, v142, v138
	v_add_u32_e32 v138, -1, v50
	v_min_u32_e32 v142, v142, v138
	v_add_u32_e32 v138, -1, v43
	v_min_u32_e32 v142, v142, v138
	v_add_u32_e32 v138, -1, v44
	v_min_u32_e32 v142, v142, v138
	s_cmp_eq_u32 s32, 4
	s_cbranch_scc1 .Lsqb_vmd
	v_add_u32_e32 v138, -1, v38
	v_min_u32_e32 v142, v142, v138
	v_add_u32_e32 v138, -1, v45
	v_min_u32_e32 v142, v142, v138
	v_add_u32_e32 v138, -1, v39
	v_min_u32_e32 v142, v142, v138
	v_add_u32_e32 v138, -1, v40
	v_min_u32_e32 v142, v142, v138
	v_add_u32_e32 v138, -1, v41
	v_min_u32_e32 v142, v142, v138
	v_add_u32_e32 v138, -1, v52
	v_min_u32_e32 v142, v142, v138
	v_add_u32_e32 v138, -1, v51
	v_min_u32_e32 v142, v142, v138
	v_add_u32_e32 v138, -1, v54
	v_min_u32_e32 v142, v142, v138
	s_cmp_eq_u32 s32, 5
	s_cbranch_scc1 .Lsqb_vmd
	v_add_u32_e32 v138, -1, v53
	v_min_u32_e32 v142, v142, v138
	v_add_u32_e32 v138, -1, v56
	v_min_u32_e32 v142, v142, v138
	v_add_u32_e32 v138, -1, v55
	v_min_u32_e32 v142, v142, v138
	v_add_u32_e32 v138, -1, v57
	v_min_u32_e32 v142, v142, v138
	v_add_u32_e32 v138, -1, v58
	v_min_u32_e32 v142, v142, v138
	v_add_u32_e32 v138, -1, v60
	v_min_u32_e32 v142, v142, v138
	v_add_u32_e32 v138, -1, v59
	v_min_u32_e32 v142, v142, v138
	v_add_u32_e32 v138, -1, v61
	v_min_u32_e32 v142, v142, v138
	v_add_u32_e32 v138, -1, v62
	v_min_u32_e32 v142, v142, v138
	v_add_u32_e32 v138, -1, v64
	v_min_u32_e32 v142, v142, v138
	v_add_u32_e32 v138, -1, v63
	v_min_u32_e32 v142, v142, v138
	v_add_u32_e32 v138, -1, v65
	v_min_u32_e32 v142, v142, v138
	v_add_u32_e32 v138, -1, v72
	v_min_u32_e32 v142, v142, v138
	v_add_u32_e32 v138, -1, v73
	v_min_u32_e32 v142, v142, v138
	v_add_u32_e32 v138, -1, v74
	v_min_u32_e32 v142, v142, v138
	v_add_u32_e32 v138, -1, v75
	v_min_u32_e32 v142, v142, v138
.Lsqb_vmd:
	v_not_b32_e32 v142, v142
	s_nop 1
	v_max_u32_dpp v142, v142, v142 row_shr:1 row_mask:0xf bank_mask:0xf bound_ctrl:1
	s_nop 1
	v_max_u32_dpp v142, v142, v142 row_shr:2 row_mask:0xf bank_mask:0xf bound_ctrl:1
	s_nop 1
	v_max_u32_dpp v142, v142, v142 row_shr:4 row_mask:0xf bank_mask:0xf bound_ctrl:1
	s_nop 1
	v_max_u32_dpp v142, v142, v142 row_shr:8 row_mask:0xf bank_mask:0xf bound_ctrl:1
	s_nop 1
	v_max_u32_dpp v142, v142, v142 row_bcast:15 row_mask:0xa bank_mask:0xf
	s_nop 1
	v_max_u32_dpp v142, v142, v142 row_bcast:31 row_mask:0xc bank_mask:0xf
	s_nop 0
	v_readlane_b32 s26, v142, 63
	s_sub_i32 s13, 0, s26
	s_mov_b32 s12, 0x80000000
	s_mov_b32 s15, s24
	s_add_i32 s26, s75, 2
	s_mov_b32 s98, s26
	s_mov_b32 s99, 1
	s_sub_i32 s27, s26, 0x100
	v_cvt_f32_u32_e32 v202, s27
	s_sub_i32 s27, s26, s24
	v_cvt_f32_u32_e32 v141, s27
	v_add_f32_e32 v202, 0.5, v202
	v_add_f32_e32 v141, 0.5, v141
	v_log_f32_e32 v202, v202
	v_log_f32_e32 v141, v141
	s_not_b32 s27, s13
	s_and_b32 s27, s27, 0x7fffffff
	s_bfe_u32 s28, s27, 0x80017
	s_sub_u32 s28, s28, 0x43
	s_cmp_lt_u32 s28, 0x79
	s_cselect_b32 s101, 1, 0
	v_add_f32_e32 v139, 1.0, v202
	v_sub_f32_e32 v141, v141, v202
	v_sqrt_f32_e32 v76, s27
	v_mov_b32_e32 v77, 0
	v_mul_f32_e32 v76, s27, v76
	s_mov_b32 s22, 0
	s_mov_b32 s23, 0
	s_mov_b32 s21, 2
	s_branch .Lsqb_next
